# speedup vs baseline: 1.0036x; 1.0014x over previous
; DEVI void st1nt(u16* p, float x) { __builtin_nontemporal_store(f2bf(x), p); }
; DEVI float siluf(float v) { return v * __builtin_amdgcn_rcpf(1.f + __expf(-v)); }
; #define EPI_ROWS(row) _Pragma("unroll") for (int m = 0; m < 8; ++m) _Pragma("unroll") for (int j = 0; j < 4; ++j) { const int row = brow + wr * 128 + m * 16 + fq * 4 + j;
; DEVI void phase_b(const Params& p, const Pass& ps, char* shm, const int wid_s_) {
;     ...
;     } else if (pn < 45) {
;       const int ch = (pn - 13) * 64 + wc * 16 + fr;
;       EPI_ROWS(row) float r = RSX[row];
;         float cx = r * acc[m][0][j], cb = r * acc[m][1][j], cc = r * acc[m][2][j], zc = r * acc[m][3][j];
;         st1nt(U + (size_t)row * DM + ch, cc * cx);
;         if (!metaT) st1nt(V2 + (size_t)row * DM + ch, cb * siluf(zc));
;       EPI_END
.LBB0_176:
	s_andn2_b64 vcc, exec, s[4:5]
	s_cbranch_vccnz .LBB0_241
	s_and_b64 vcc, exec, s[8:9]
	s_cbranch_vccz .Lconv_slow
	v_lshl_add_u32 v146, v141, 7, s17
	v_lshl_or_b32 v146, v139, 2, v146
	v_lshlrev_b32_e32 v159, 2, v146
	global_load_dword v160, v159, s[42:43]
	global_load_dword v161, v159, s[42:43] offset:4
	global_load_dword v162, v159, s[42:43] offset:8
	global_load_dword v163, v159, s[42:43] offset:12
	global_load_dword v164, v159, s[42:43] offset:64
	global_load_dword v165, v159, s[42:43] offset:68
	global_load_dword v166, v159, s[42:43] offset:72
	global_load_dword v167, v159, s[42:43] offset:76
	global_load_dword v168, v159, s[42:43] offset:128
	global_load_dword v169, v159, s[42:43] offset:132
	global_load_dword v170, v159, s[42:43] offset:136
	global_load_dword v171, v159, s[42:43] offset:140
	global_load_dword v172, v159, s[42:43] offset:192
	global_load_dword v173, v159, s[42:43] offset:196
	global_load_dword v174, v159, s[42:43] offset:200
	global_load_dword v175, v159, s[42:43] offset:204
	global_load_dword v176, v159, s[42:43] offset:256
	global_load_dword v177, v159, s[42:43] offset:260
	global_load_dword v178, v159, s[42:43] offset:264
	global_load_dword v179, v159, s[42:43] offset:268
	global_load_dword v180, v159, s[42:43] offset:320
	global_load_dword v181, v159, s[42:43] offset:324
	global_load_dword v182, v159, s[42:43] offset:328
	global_load_dword v183, v159, s[42:43] offset:332
	global_load_dword v184, v159, s[42:43] offset:384
	global_load_dword v185, v159, s[42:43] offset:388
	global_load_dword v186, v159, s[42:43] offset:392
	global_load_dword v187, v159, s[42:43] offset:396
	global_load_dword v188, v159, s[42:43] offset:448
	global_load_dword v189, v159, s[42:43] offset:452
	global_load_dword v190, v159, s[42:43] offset:456
	global_load_dword v191, v159, s[42:43] offset:460
	s_lshl_b32 s1, s46, 6
	s_addk_i32 s1, 0xfcc0
	v_lshlrev_b32_e32 v147, 4, v140
	v_or3_b32 v147, v147, s1, v138
	v_lshlrev_b32_e32 v147, 1, v147
	v_lshl_add_u32 v146, v146, 12, v147
	s_waitcnt vmcnt(0)
	v_mov_b32_e32 v148, v146
	v_add_u32_e32 v149, 0x1000, v146
	v_mul_f32_e32 v120, v120, v160
	v_mul_f32_e32 v121, v121, v161
	v_mul_f32_e32 v112, v112, v160
	v_mul_f32_e32 v113, v113, v161
	v_mul_f32_e32 v116, v116, v160
	v_mul_f32_e32 v117, v117, v161
	v_mul_f32_e32 v124, v124, v160
	v_mul_f32_e32 v125, v125, v161
	v_mul_f32_e32 v120, v120, v112
	v_mul_f32_e32 v121, v121, v113
	v_mul_f32_e32 v112, 0xbfb8aa3b, v116
	v_mul_f32_e32 v113, 0xbfb8aa3b, v117
	v_exp_f32_e32 v112, v112
	v_exp_f32_e32 v113, v113
	v_cvt_pk_bf16_f32 v120, v120, s0
	v_cvt_pk_bf16_f32 v121, v121, s0
	v_add_f32_e32 v112, 1.0, v112
	v_add_f32_e32 v113, 1.0, v113
	v_rcp_f32_e32 v112, v112
	v_rcp_f32_e32 v113, v113
	global_store_short v148, v120, s[50:51] nt
	global_store_short v149, v121, s[50:51] nt
	v_mul_f32_e32 v116, v116, v112
	v_mul_f32_e32 v117, v117, v113
	v_mul_f32_e32 v124, v124, v116
	v_mul_f32_e32 v125, v125, v117
	v_cvt_pk_bf16_f32 v124, v124, s0
	v_cvt_pk_bf16_f32 v125, v125, s0
	global_store_short v148, v124, s[52:53] nt
	global_store_short v149, v125, s[52:53] nt
	v_add_u32_e32 v148, 0x2000, v146
	v_add_u32_e32 v149, 0x3000, v146
	v_mul_f32_e32 v122, v122, v162
	v_mul_f32_e32 v123, v123, v163
	v_mul_f32_e32 v114, v114, v162
	v_mul_f32_e32 v115, v115, v163
	v_mul_f32_e32 v118, v118, v162
	v_mul_f32_e32 v119, v119, v163
	v_mul_f32_e32 v126, v126, v162
	v_mul_f32_e32 v127, v127, v163
	v_mul_f32_e32 v122, v122, v114
	v_mul_f32_e32 v123, v123, v115
	v_mul_f32_e32 v114, 0xbfb8aa3b, v118
	v_mul_f32_e32 v115, 0xbfb8aa3b, v119
	v_exp_f32_e32 v114, v114
	v_exp_f32_e32 v115, v115
	v_cvt_pk_bf16_f32 v122, v122, s0
	v_cvt_pk_bf16_f32 v123, v123, s0
	v_add_f32_e32 v114, 1.0, v114
	v_add_f32_e32 v115, 1.0, v115
	v_rcp_f32_e32 v114, v114
	v_rcp_f32_e32 v115, v115
	global_store_short v148, v122, s[50:51] nt
	global_store_short v149, v123, s[50:51] nt
	v_mul_f32_e32 v118, v118, v114
	v_mul_f32_e32 v119, v119, v115
	v_mul_f32_e32 v126, v126, v118
	v_mul_f32_e32 v127, v127, v119
	v_cvt_pk_bf16_f32 v126, v126, s0
	v_cvt_pk_bf16_f32 v127, v127, s0
	global_store_short v148, v126, s[52:53] nt
	global_store_short v149, v127, s[52:53] nt
	v_add_u32_e32 v148, 0x10000, v146
	v_add_u32_e32 v149, 0x11000, v146
	v_mul_f32_e32 v104, v104, v164
	v_mul_f32_e32 v105, v105, v165
	v_mul_f32_e32 v96, v96, v164
	v_mul_f32_e32 v97, v97, v165
	v_mul_f32_e32 v100, v100, v164
	v_mul_f32_e32 v101, v101, v165
	v_mul_f32_e32 v108, v108, v164
	v_mul_f32_e32 v109, v109, v165
	v_mul_f32_e32 v104, v104, v96
	v_mul_f32_e32 v105, v105, v97
	v_mul_f32_e32 v96, 0xbfb8aa3b, v100
	v_mul_f32_e32 v97, 0xbfb8aa3b, v101
	v_exp_f32_e32 v96, v96
	v_exp_f32_e32 v97, v97
	v_cvt_pk_bf16_f32 v104, v104, s0
	v_cvt_pk_bf16_f32 v105, v105, s0
	v_add_f32_e32 v96, 1.0, v96
	v_add_f32_e32 v97, 1.0, v97
	v_rcp_f32_e32 v96, v96
	v_rcp_f32_e32 v97, v97
	global_store_short v148, v104, s[50:51] nt
	global_store_short v149, v105, s[50:51] nt
	v_mul_f32_e32 v100, v100, v96
	v_mul_f32_e32 v101, v101, v97
	v_mul_f32_e32 v108, v108, v100
	v_mul_f32_e32 v109, v109, v101
	v_cvt_pk_bf16_f32 v108, v108, s0
	v_cvt_pk_bf16_f32 v109, v109, s0
	global_store_short v148, v108, s[52:53] nt
	global_store_short v149, v109, s[52:53] nt
	v_add_u32_e32 v148, 0x12000, v146
	v_add_u32_e32 v149, 0x13000, v146
	v_mul_f32_e32 v106, v106, v166
	v_mul_f32_e32 v107, v107, v167
	v_mul_f32_e32 v98, v98, v166
	v_mul_f32_e32 v99, v99, v167
	v_mul_f32_e32 v102, v102, v166
	v_mul_f32_e32 v103, v103, v167
	v_mul_f32_e32 v110, v110, v166
	v_mul_f32_e32 v111, v111, v167
	v_mul_f32_e32 v106, v106, v98
	v_mul_f32_e32 v107, v107, v99
	v_mul_f32_e32 v98, 0xbfb8aa3b, v102
; DEVI void st1nt(u16* p, float x) { __builtin_nontemporal_store(f2bf(x), p); }
; DEVI float siluf(float v) { return v * __builtin_amdgcn_rcpf(1.f + __expf(-v)); }
; #define EPI_ROWS(row) _Pragma("unroll") for (int m = 0; m < 8; ++m) _Pragma("unroll") for (int j = 0; j < 4; ++j) { const int row = brow + wr * 128 + m * 16 + fq * 4 + j;
; DEVI void phase_b(const Params& p, const Pass& ps, char* shm, const int wid_s_) {
;     ...
;     } else if (pn < 45) {
;       const int ch = (pn - 13) * 64 + wc * 16 + fr;
;       EPI_ROWS(row) float r = RSX[row];
;         float cx = r * acc[m][0][j], cb = r * acc[m][1][j], cc = r * acc[m][2][j], zc = r * acc[m][3][j];
;         st1nt(U + (size_t)row * DM + ch, cc * cx);
;         if (!metaT) st1nt(V2 + (size_t)row * DM + ch, cb * siluf(zc));
;       EPI_END
	v_mul_f32_e32 v99, 0xbfb8aa3b, v103
	v_exp_f32_e32 v98, v98
	v_exp_f32_e32 v99, v99
	v_cvt_pk_bf16_f32 v106, v106, s0
	v_cvt_pk_bf16_f32 v107, v107, s0
	v_add_f32_e32 v98, 1.0, v98
	v_add_f32_e32 v99, 1.0, v99
	v_rcp_f32_e32 v98, v98
	v_rcp_f32_e32 v99, v99
	global_store_short v148, v106, s[50:51] nt
	global_store_short v149, v107, s[50:51] nt
	v_mul_f32_e32 v102, v102, v98
	v_mul_f32_e32 v103, v103, v99
	v_mul_f32_e32 v110, v110, v102
	v_mul_f32_e32 v111, v111, v103
	v_cvt_pk_bf16_f32 v110, v110, s0
	v_cvt_pk_bf16_f32 v111, v111, s0
	global_store_short v148, v110, s[52:53] nt
	global_store_short v149, v111, s[52:53] nt
	v_add_u32_e32 v148, 0x20000, v146
	v_add_u32_e32 v149, 0x21000, v146
	v_mul_f32_e32 v88, v88, v168
	v_mul_f32_e32 v89, v89, v169
	v_mul_f32_e32 v80, v80, v168
	v_mul_f32_e32 v81, v81, v169
	v_mul_f32_e32 v84, v84, v168
	v_mul_f32_e32 v85, v85, v169
	v_mul_f32_e32 v92, v92, v168
	v_mul_f32_e32 v93, v93, v169
	v_mul_f32_e32 v88, v88, v80
	v_mul_f32_e32 v89, v89, v81
	v_mul_f32_e32 v80, 0xbfb8aa3b, v84
	v_mul_f32_e32 v81, 0xbfb8aa3b, v85
	v_exp_f32_e32 v80, v80
	v_exp_f32_e32 v81, v81
	v_cvt_pk_bf16_f32 v88, v88, s0
	v_cvt_pk_bf16_f32 v89, v89, s0
	v_add_f32_e32 v80, 1.0, v80
	v_add_f32_e32 v81, 1.0, v81
	v_rcp_f32_e32 v80, v80
	v_rcp_f32_e32 v81, v81
	global_store_short v148, v88, s[50:51] nt
	global_store_short v149, v89, s[50:51] nt
	v_mul_f32_e32 v84, v84, v80
	v_mul_f32_e32 v85, v85, v81
	v_mul_f32_e32 v92, v92, v84
	v_mul_f32_e32 v93, v93, v85
	v_cvt_pk_bf16_f32 v92, v92, s0
	v_cvt_pk_bf16_f32 v93, v93, s0
	global_store_short v148, v92, s[52:53] nt
	global_store_short v149, v93, s[52:53] nt
	v_add_u32_e32 v148, 0x22000, v146
	v_add_u32_e32 v149, 0x23000, v146
	v_mul_f32_e32 v90, v90, v170
	v_mul_f32_e32 v91, v91, v171
	v_mul_f32_e32 v82, v82, v170
	v_mul_f32_e32 v83, v83, v171
	v_mul_f32_e32 v86, v86, v170
	v_mul_f32_e32 v87, v87, v171
	v_mul_f32_e32 v94, v94, v170
	v_mul_f32_e32 v95, v95, v171
	v_mul_f32_e32 v90, v90, v82
	v_mul_f32_e32 v91, v91, v83
	v_mul_f32_e32 v82, 0xbfb8aa3b, v86
	v_mul_f32_e32 v83, 0xbfb8aa3b, v87
	v_exp_f32_e32 v82, v82
	v_exp_f32_e32 v83, v83
	v_cvt_pk_bf16_f32 v90, v90, s0
	v_cvt_pk_bf16_f32 v91, v91, s0
	v_add_f32_e32 v82, 1.0, v82
	v_add_f32_e32 v83, 1.0, v83
	v_rcp_f32_e32 v82, v82
	v_rcp_f32_e32 v83, v83
	global_store_short v148, v90, s[50:51] nt
	global_store_short v149, v91, s[50:51] nt
	v_mul_f32_e32 v86, v86, v82
	v_mul_f32_e32 v87, v87, v83
	v_mul_f32_e32 v94, v94, v86
	v_mul_f32_e32 v95, v95, v87
	v_cvt_pk_bf16_f32 v94, v94, s0
	v_cvt_pk_bf16_f32 v95, v95, s0
	global_store_short v148, v94, s[52:53] nt
	global_store_short v149, v95, s[52:53] nt
	v_add_u32_e32 v148, 0x30000, v146
	v_add_u32_e32 v149, 0x31000, v146
	v_mul_f32_e32 v72, v72, v172
	v_mul_f32_e32 v73, v73, v173
	v_mul_f32_e32 v64, v64, v172
	v_mul_f32_e32 v65, v65, v173
	v_mul_f32_e32 v68, v68, v172
	v_mul_f32_e32 v69, v69, v173
	v_mul_f32_e32 v76, v76, v172
	v_mul_f32_e32 v77, v77, v173
	v_mul_f32_e32 v72, v72, v64
	v_mul_f32_e32 v73, v73, v65
	v_mul_f32_e32 v64, 0xbfb8aa3b, v68
	v_mul_f32_e32 v65, 0xbfb8aa3b, v69
	v_exp_f32_e32 v64, v64
	v_exp_f32_e32 v65, v65
	v_cvt_pk_bf16_f32 v72, v72, s0
	v_cvt_pk_bf16_f32 v73, v73, s0
	v_add_f32_e32 v64, 1.0, v64
	v_add_f32_e32 v65, 1.0, v65
	v_rcp_f32_e32 v64, v64
	v_rcp_f32_e32 v65, v65
	global_store_short v148, v72, s[50:51] nt
	global_store_short v149, v73, s[50:51] nt
	v_mul_f32_e32 v68, v68, v64
	v_mul_f32_e32 v69, v69, v65
	v_mul_f32_e32 v76, v76, v68
	v_mul_f32_e32 v77, v77, v69
	v_cvt_pk_bf16_f32 v76, v76, s0
	v_cvt_pk_bf16_f32 v77, v77, s0
	global_store_short v148, v76, s[52:53] nt
	global_store_short v149, v77, s[52:53] nt
	v_add_u32_e32 v148, 0x32000, v146
	v_add_u32_e32 v149, 0x33000, v146
	v_mul_f32_e32 v74, v74, v174
	v_mul_f32_e32 v75, v75, v175
	v_mul_f32_e32 v66, v66, v174
	v_mul_f32_e32 v67, v67, v175
	v_mul_f32_e32 v70, v70, v174
	v_mul_f32_e32 v71, v71, v175
	v_mul_f32_e32 v78, v78, v174
	v_mul_f32_e32 v79, v79, v175
	v_mul_f32_e32 v74, v74, v66
	v_mul_f32_e32 v75, v75, v67
	v_mul_f32_e32 v66, 0xbfb8aa3b, v70
	v_mul_f32_e32 v67, 0xbfb8aa3b, v71
	v_exp_f32_e32 v66, v66
	v_exp_f32_e32 v67, v67
	v_cvt_pk_bf16_f32 v74, v74, s0
	v_cvt_pk_bf16_f32 v75, v75, s0
	v_add_f32_e32 v66, 1.0, v66
	v_add_f32_e32 v67, 1.0, v67
	v_rcp_f32_e32 v66, v66
	v_rcp_f32_e32 v67, v67
	global_store_short v148, v74, s[50:51] nt
	global_store_short v149, v75, s[50:51] nt
	v_mul_f32_e32 v70, v70, v66
	v_mul_f32_e32 v71, v71, v67
	v_mul_f32_e32 v78, v78, v70
	v_mul_f32_e32 v79, v79, v71
	v_cvt_pk_bf16_f32 v78, v78, s0
	v_cvt_pk_bf16_f32 v79, v79, s0
	global_store_short v148, v78, s[52:53] nt
	global_store_short v149, v79, s[52:53] nt
	v_add_u32_e32 v148, 0x40000, v146
	v_add_u32_e32 v149, 0x41000, v146
	v_mul_f32_e32 v56, v56, v176
	v_mul_f32_e32 v57, v57, v177
	v_mul_f32_e32 v48, v48, v176
	v_mul_f32_e32 v49, v49, v177
	v_mul_f32_e32 v52, v52, v176
	v_mul_f32_e32 v53, v53, v177
	v_mul_f32_e32 v60, v60, v176
	v_mul_f32_e32 v61, v61, v177
	v_mul_f32_e32 v56, v56, v48
	v_mul_f32_e32 v57, v57, v49
	v_mul_f32_e32 v48, 0xbfb8aa3b, v52
	v_mul_f32_e32 v49, 0xbfb8aa3b, v53
	v_exp_f32_e32 v48, v48
	v_exp_f32_e32 v49, v49
	v_cvt_pk_bf16_f32 v56, v56, s0
	v_cvt_pk_bf16_f32 v57, v57, s0
	v_add_f32_e32 v48, 1.0, v48
	v_add_f32_e32 v49, 1.0, v49
	v_rcp_f32_e32 v48, v48
	v_rcp_f32_e32 v49, v49
	global_store_short v148, v56, s[50:51] nt
	global_store_short v149, v57, s[50:51] nt
	v_mul_f32_e32 v52, v52, v48
	v_mul_f32_e32 v53, v53, v49
	v_mul_f32_e32 v60, v60, v52
	v_mul_f32_e32 v61, v61, v53
	v_cvt_pk_bf16_f32 v60, v60, s0
	v_cvt_pk_bf16_f32 v61, v61, s0
	global_store_short v148, v60, s[52:53] nt
; DEVI void st1nt(u16* p, float x) { __builtin_nontemporal_store(f2bf(x), p); }
; DEVI float siluf(float v) { return v * __builtin_amdgcn_rcpf(1.f + __expf(-v)); }
; #define EPI_ROWS(row) _Pragma("unroll") for (int m = 0; m < 8; ++m) _Pragma("unroll") for (int j = 0; j < 4; ++j) { const int row = brow + wr * 128 + m * 16 + fq * 4 + j;
; DEVI void phase_b(const Params& p, const Pass& ps, char* shm, const int wid_s_) {
;     ...
;     } else if (pn < 45) {
;       const int ch = (pn - 13) * 64 + wc * 16 + fr;
;       EPI_ROWS(row) float r = RSX[row];
;         float cx = r * acc[m][0][j], cb = r * acc[m][1][j], cc = r * acc[m][2][j], zc = r * acc[m][3][j];
;         st1nt(U + (size_t)row * DM + ch, cc * cx);
;         if (!metaT) st1nt(V2 + (size_t)row * DM + ch, cb * siluf(zc));
;       EPI_END
	global_store_short v149, v61, s[52:53] nt
	v_add_u32_e32 v148, 0x42000, v146
	v_add_u32_e32 v149, 0x43000, v146
	v_mul_f32_e32 v58, v58, v178
	v_mul_f32_e32 v59, v59, v179
	v_mul_f32_e32 v50, v50, v178
	v_mul_f32_e32 v51, v51, v179
	v_mul_f32_e32 v54, v54, v178
	v_mul_f32_e32 v55, v55, v179
	v_mul_f32_e32 v62, v62, v178
	v_mul_f32_e32 v63, v63, v179
	v_mul_f32_e32 v58, v58, v50
	v_mul_f32_e32 v59, v59, v51
	v_mul_f32_e32 v50, 0xbfb8aa3b, v54
	v_mul_f32_e32 v51, 0xbfb8aa3b, v55
	v_exp_f32_e32 v50, v50
	v_exp_f32_e32 v51, v51
	v_cvt_pk_bf16_f32 v58, v58, s0
	v_cvt_pk_bf16_f32 v59, v59, s0
	v_add_f32_e32 v50, 1.0, v50
	v_add_f32_e32 v51, 1.0, v51
	v_rcp_f32_e32 v50, v50
	v_rcp_f32_e32 v51, v51
	global_store_short v148, v58, s[50:51] nt
	global_store_short v149, v59, s[50:51] nt
	v_mul_f32_e32 v54, v54, v50
	v_mul_f32_e32 v55, v55, v51
	v_mul_f32_e32 v62, v62, v54
	v_mul_f32_e32 v63, v63, v55
	v_cvt_pk_bf16_f32 v62, v62, s0
	v_cvt_pk_bf16_f32 v63, v63, s0
	global_store_short v148, v62, s[52:53] nt
	global_store_short v149, v63, s[52:53] nt
	v_add_u32_e32 v148, 0x50000, v146
	v_add_u32_e32 v149, 0x51000, v146
	v_mul_f32_e32 v40, v40, v180
	v_mul_f32_e32 v41, v41, v181
	v_mul_f32_e32 v32, v32, v180
	v_mul_f32_e32 v33, v33, v181
	v_mul_f32_e32 v36, v36, v180
	v_mul_f32_e32 v37, v37, v181
	v_mul_f32_e32 v44, v44, v180
	v_mul_f32_e32 v45, v45, v181
	v_mul_f32_e32 v40, v40, v32
	v_mul_f32_e32 v41, v41, v33
	v_mul_f32_e32 v32, 0xbfb8aa3b, v36
	v_mul_f32_e32 v33, 0xbfb8aa3b, v37
	v_exp_f32_e32 v32, v32
	v_exp_f32_e32 v33, v33
	v_cvt_pk_bf16_f32 v40, v40, s0
	v_cvt_pk_bf16_f32 v41, v41, s0
	v_add_f32_e32 v32, 1.0, v32
	v_add_f32_e32 v33, 1.0, v33
	v_rcp_f32_e32 v32, v32
	v_rcp_f32_e32 v33, v33
	global_store_short v148, v40, s[50:51] nt
	global_store_short v149, v41, s[50:51] nt
	v_mul_f32_e32 v36, v36, v32
	v_mul_f32_e32 v37, v37, v33
	v_mul_f32_e32 v44, v44, v36
	v_mul_f32_e32 v45, v45, v37
	v_cvt_pk_bf16_f32 v44, v44, s0
	v_cvt_pk_bf16_f32 v45, v45, s0
	global_store_short v148, v44, s[52:53] nt
	global_store_short v149, v45, s[52:53] nt
	v_add_u32_e32 v148, 0x52000, v146
	v_add_u32_e32 v149, 0x53000, v146
	v_mul_f32_e32 v42, v42, v182
	v_mul_f32_e32 v43, v43, v183
	v_mul_f32_e32 v34, v34, v182
	v_mul_f32_e32 v35, v35, v183
	v_mul_f32_e32 v38, v38, v182
	v_mul_f32_e32 v39, v39, v183
	v_mul_f32_e32 v46, v46, v182
	v_mul_f32_e32 v47, v47, v183
	v_mul_f32_e32 v42, v42, v34
	v_mul_f32_e32 v43, v43, v35
	v_mul_f32_e32 v34, 0xbfb8aa3b, v38
	v_mul_f32_e32 v35, 0xbfb8aa3b, v39
	v_exp_f32_e32 v34, v34
	v_exp_f32_e32 v35, v35
	v_cvt_pk_bf16_f32 v42, v42, s0
	v_cvt_pk_bf16_f32 v43, v43, s0
	v_add_f32_e32 v34, 1.0, v34
	v_add_f32_e32 v35, 1.0, v35
	v_rcp_f32_e32 v34, v34
	v_rcp_f32_e32 v35, v35
	global_store_short v148, v42, s[50:51] nt
	global_store_short v149, v43, s[50:51] nt
	v_mul_f32_e32 v38, v38, v34
	v_mul_f32_e32 v39, v39, v35
	v_mul_f32_e32 v46, v46, v38
	v_mul_f32_e32 v47, v47, v39
	v_cvt_pk_bf16_f32 v46, v46, s0
	v_cvt_pk_bf16_f32 v47, v47, s0
	global_store_short v148, v46, s[52:53] nt
	global_store_short v149, v47, s[52:53] nt
	v_add_u32_e32 v148, 0x60000, v146
	v_add_u32_e32 v149, 0x61000, v146
	v_mul_f32_e32 v20, v20, v184
	v_mul_f32_e32 v21, v21, v185
	v_mul_f32_e32 v16, v16, v184
	v_mul_f32_e32 v17, v17, v185
	v_mul_f32_e32 v28, v28, v184
	v_mul_f32_e32 v29, v29, v185
	v_mul_f32_e32 v24, v24, v184
	v_mul_f32_e32 v25, v25, v185
	v_mul_f32_e32 v20, v20, v16
	v_mul_f32_e32 v21, v21, v17
	v_mul_f32_e32 v16, 0xbfb8aa3b, v28
	v_mul_f32_e32 v17, 0xbfb8aa3b, v29
	v_exp_f32_e32 v16, v16
	v_exp_f32_e32 v17, v17
	v_cvt_pk_bf16_f32 v20, v20, s0
	v_cvt_pk_bf16_f32 v21, v21, s0
	v_add_f32_e32 v16, 1.0, v16
	v_add_f32_e32 v17, 1.0, v17
	v_rcp_f32_e32 v16, v16
	v_rcp_f32_e32 v17, v17
	global_store_short v148, v20, s[50:51] nt
	global_store_short v149, v21, s[50:51] nt
	v_mul_f32_e32 v28, v28, v16
	v_mul_f32_e32 v29, v29, v17
	v_mul_f32_e32 v24, v24, v28
	v_mul_f32_e32 v25, v25, v29
	v_cvt_pk_bf16_f32 v24, v24, s0
	v_cvt_pk_bf16_f32 v25, v25, s0
	global_store_short v148, v24, s[52:53] nt
	global_store_short v149, v25, s[52:53] nt
	v_add_u32_e32 v148, 0x62000, v146
	v_add_u32_e32 v149, 0x63000, v146
	v_mul_f32_e32 v22, v22, v186
	v_mul_f32_e32 v23, v23, v187
	v_mul_f32_e32 v18, v18, v186
	v_mul_f32_e32 v19, v19, v187
	v_mul_f32_e32 v30, v30, v186
	v_mul_f32_e32 v31, v31, v187
	v_mul_f32_e32 v26, v26, v186
	v_mul_f32_e32 v27, v27, v187
	v_mul_f32_e32 v22, v22, v18
	v_mul_f32_e32 v23, v23, v19
	v_mul_f32_e32 v18, 0xbfb8aa3b, v30
	v_mul_f32_e32 v19, 0xbfb8aa3b, v31
	v_exp_f32_e32 v18, v18
	v_exp_f32_e32 v19, v19
	v_cvt_pk_bf16_f32 v22, v22, s0
	v_cvt_pk_bf16_f32 v23, v23, s0
	v_add_f32_e32 v18, 1.0, v18
	v_add_f32_e32 v19, 1.0, v19
	v_rcp_f32_e32 v18, v18
	v_rcp_f32_e32 v19, v19
	global_store_short v148, v22, s[50:51] nt
	global_store_short v149, v23, s[50:51] nt
	v_mul_f32_e32 v30, v30, v18
	v_mul_f32_e32 v31, v31, v19
	v_mul_f32_e32 v26, v26, v30
	v_mul_f32_e32 v27, v27, v31
	v_cvt_pk_bf16_f32 v26, v26, s0
	v_cvt_pk_bf16_f32 v27, v27, s0
	global_store_short v148, v26, s[52:53] nt
; DEVI void st1nt(u16* p, float x) { __builtin_nontemporal_store(f2bf(x), p); }
; DEVI float siluf(float v) { return v * __builtin_amdgcn_rcpf(1.f + __expf(-v)); }
; #define EPI_ROWS(row) _Pragma("unroll") for (int m = 0; m < 8; ++m) _Pragma("unroll") for (int j = 0; j < 4; ++j) { const int row = brow + wr * 128 + m * 16 + fq * 4 + j;
; DEVI void phase_b(const Params& p, const Pass& ps, char* shm, const int wid_s_) {
;     ...
;     } else if (pn < 45) {
;       const int ch = (pn - 13) * 64 + wc * 16 + fr;
;       EPI_ROWS(row) float r = RSX[row];
;         float cx = r * acc[m][0][j], cb = r * acc[m][1][j], cc = r * acc[m][2][j], zc = r * acc[m][3][j];
;         st1nt(U + (size_t)row * DM + ch, cc * cx);
;         if (!metaT) st1nt(V2 + (size_t)row * DM + ch, cb * siluf(zc));
;       EPI_END
	global_store_short v149, v27, s[52:53] nt
	v_add_u32_e32 v148, 0x70000, v146
	v_add_u32_e32 v149, 0x71000, v146
	v_mul_f32_e32 v8, v8, v188
	v_mul_f32_e32 v9, v9, v189
	v_mul_f32_e32 v4, v4, v188
	v_mul_f32_e32 v5, v5, v189
	v_mul_f32_e32 v0, v0, v188
	v_mul_f32_e32 v1, v1, v189
	v_mul_f32_e32 v12, v12, v188
	v_mul_f32_e32 v13, v13, v189
	v_mul_f32_e32 v8, v8, v4
	v_mul_f32_e32 v9, v9, v5
	v_mul_f32_e32 v4, 0xbfb8aa3b, v0
	v_mul_f32_e32 v5, 0xbfb8aa3b, v1
	v_exp_f32_e32 v4, v4
	v_exp_f32_e32 v5, v5
	v_cvt_pk_bf16_f32 v8, v8, s0
	v_cvt_pk_bf16_f32 v9, v9, s0
	v_add_f32_e32 v4, 1.0, v4
	v_add_f32_e32 v5, 1.0, v5
	v_rcp_f32_e32 v4, v4
	v_rcp_f32_e32 v5, v5
	global_store_short v148, v8, s[50:51] nt
	global_store_short v149, v9, s[50:51] nt
	v_mul_f32_e32 v0, v0, v4
	v_mul_f32_e32 v1, v1, v5
	v_mul_f32_e32 v12, v12, v0
	v_mul_f32_e32 v13, v13, v1
	v_cvt_pk_bf16_f32 v12, v12, s0
	v_cvt_pk_bf16_f32 v13, v13, s0
	global_store_short v148, v12, s[52:53] nt
	global_store_short v149, v13, s[52:53] nt
	v_add_u32_e32 v148, 0x72000, v146
	v_add_u32_e32 v149, 0x73000, v146
	v_mul_f32_e32 v10, v10, v190
	v_mul_f32_e32 v11, v11, v191
	v_mul_f32_e32 v6, v6, v190
	v_mul_f32_e32 v7, v7, v191
	v_mul_f32_e32 v2, v2, v190
	v_mul_f32_e32 v3, v3, v191
	v_mul_f32_e32 v14, v14, v190
	v_mul_f32_e32 v15, v15, v191
	v_mul_f32_e32 v10, v10, v6
	v_mul_f32_e32 v11, v11, v7
	v_mul_f32_e32 v6, 0xbfb8aa3b, v2
	v_mul_f32_e32 v7, 0xbfb8aa3b, v3
	v_exp_f32_e32 v6, v6
	v_exp_f32_e32 v7, v7
	v_cvt_pk_bf16_f32 v10, v10, s0
	v_cvt_pk_bf16_f32 v11, v11, s0
	v_add_f32_e32 v6, 1.0, v6
	v_add_f32_e32 v7, 1.0, v7
	v_rcp_f32_e32 v6, v6
	v_rcp_f32_e32 v7, v7
	global_store_short v148, v10, s[50:51] nt
	global_store_short v149, v11, s[50:51] nt
	v_mul_f32_e32 v2, v2, v6
	v_mul_f32_e32 v3, v3, v7
	v_mul_f32_e32 v14, v14, v2
	v_mul_f32_e32 v15, v15, v3
	v_cvt_pk_bf16_f32 v14, v14, s0
	v_cvt_pk_bf16_f32 v15, v15, s0
	global_store_short v148, v14, s[52:53] nt
	global_store_short v149, v15, s[52:53] nt
	s_branch .LBB0_241
.Lconv_slow:
	v_lshl_add_u32 v128, v141, 7, s17
	v_lshl_or_b32 v130, v139, 2, v128
	v_ashrrev_i32_e32 v131, 31, v130
	v_lshl_add_u64 v[128:129], v[130:131], 2, s[42:43]
	v_lshlrev_b32_e32 v159, 2, v130
	global_load_dword v160, v159, s[42:43]
	global_load_dword v161, v159, s[42:43] offset:4
	global_load_dword v162, v159, s[42:43] offset:8
	global_load_dword v163, v159, s[42:43] offset:12
	global_load_dword v164, v159, s[42:43] offset:64
	global_load_dword v165, v159, s[42:43] offset:68
	global_load_dword v166, v159, s[42:43] offset:72
	global_load_dword v167, v159, s[42:43] offset:76
	global_load_dword v168, v159, s[42:43] offset:128
	global_load_dword v169, v159, s[42:43] offset:132
	global_load_dword v170, v159, s[42:43] offset:136
	global_load_dword v171, v159, s[42:43] offset:140
	global_load_dword v172, v159, s[42:43] offset:192
	global_load_dword v173, v159, s[42:43] offset:196
	global_load_dword v174, v159, s[42:43] offset:200
	global_load_dword v175, v159, s[42:43] offset:204
	global_load_dword v176, v159, s[42:43] offset:256
	global_load_dword v177, v159, s[42:43] offset:260
	global_load_dword v178, v159, s[42:43] offset:264
	global_load_dword v179, v159, s[42:43] offset:268
	global_load_dword v180, v159, s[42:43] offset:320
	global_load_dword v181, v159, s[42:43] offset:324
	global_load_dword v182, v159, s[42:43] offset:328
	global_load_dword v183, v159, s[42:43] offset:332
	global_load_dword v184, v159, s[42:43] offset:384
	global_load_dword v185, v159, s[42:43] offset:388
	global_load_dword v186, v159, s[42:43] offset:392
	global_load_dword v187, v159, s[42:43] offset:396
	global_load_dword v188, v159, s[42:43] offset:448
	global_load_dword v189, v159, s[42:43] offset:452
	global_load_dword v190, v159, s[42:43] offset:456
	global_load_dword v191, v159, s[42:43] offset:460
	s_waitcnt vmcnt(0)
	v_mov_b32_e32 v134, v160
	s_lshl_b32 s1, s46, 6
	v_lshlrev_b32_e32 v128, 4, v140
	s_addk_i32 s1, 0xfcc0
	v_mov_b32_e32 v136, v120
	v_mov_b32_e32 v137, v112
	v_cndmask_b32_e64 v129, 0, 1, s[8:9]
	v_or3_b32 v204, v128, s1, v138
	v_cmp_ne_u32_e64 s[4:5], 1, v129
	v_lshlrev_b64 v[128:129], 1, v[204:205]
	v_lshlrev_b64 v[142:143], 12, v[130:131]
	v_lshl_add_u64 v[132:133], s[50:51], 0, v[128:129]
	v_lshl_add_u64 v[128:129], s[52:53], 0, v[128:129]
	v_lshl_add_u64 v[142:143], v[132:133], 0, v[142:143]
	s_andn2_b64 vcc, exec, s[8:9]
	v_pk_mul_f32 v[136:137], v[136:137], v[134:135] op_sel_hi:[1,0]
	s_nop 0
	v_mul_f32_e32 v135, v136, v137
	v_cvt_pk_bf16_f32 v135, v135, s0
	global_store_short v[142:143], v135, off nt
	s_cbranch_vccnz .LBB0_179
	v_mov_b32_e32 v135, v134
	v_mov_b32_e32 v136, v124
	v_mov_b32_e32 v137, v116
	v_pk_mul_f32 v[134:135], v[136:137], v[134:135]
	s_nop 0
	v_mul_f32_e32 v136, 0xbfb8aa3b, v135
	v_exp_f32_e32 v136, v136
	s_nop 0
	v_add_f32_e32 v136, 1.0, v136
	v_rcp_f32_e32 v142, v136
	v_lshlrev_b64 v[136:137], 11, v[130:131]
	v_lshl_add_u64 v[136:137], v[136:137], 1, v[128:129]
	v_mul_f32_e32 v131, v135, v142
	v_mul_f32_e32 v131, v134, v131
	v_cvt_pk_bf16_f32 v131, v131, s0
	global_store_short v[136:137], v131, off nt
